# v015 + attention prologues no longer wait for the Q fragment loads before the ring barrier / first tile requests
# baseline (speedup 1.0000x reference)
.LBB0_342:
	s_and_b64 s[24:25], s[36:37], exec
	s_cselect_b32 s54, s44, s45
	s_ashr_i32 s55, s54, 6
	s_sub_i32 s4, 7, s55
	s_lshl_b32 s24, s4, 8
	s_add_i32 s24, s24, s40
	s_lshl_b32 s53, s4, 2
	s_lshl_b32 s4, s54, 9
	s_add_i32 s52, s53, s41
	s_and_b32 s26, s4, 0x7800
	s_ashr_i32 s4, s24, 31
	s_add_u32 s57, s24, s26
	s_addc_u32 s58, s4, 0
	s_lshl_b32 s4, s54, 7
	s_mul_i32 s24, s58, 0x1800
	s_mul_hi_u32 s25, s57, 0x1800
	s_and_b32 s4, s4, 0x180
	s_add_i32 s25, s25, s24
	s_mul_i32 s24, s57, 0x1800
	s_add_u32 s24, s10, s24
	s_addc_u32 s25, s11, s25
	s_lshl_b32 s4, s4, 1
	s_add_u32 s24, s24, s4
	s_addc_u32 s25, s25, 0
	v_lshl_add_u64 v[2:3], s[24:25], 0, v[132:133]
	v_lshl_add_u64 v[128:129], v[2:3], 0, v[134:135]
	global_load_dwordx4 v[112:115], v[128:129], off
	global_load_dwordx4 v[116:119], v[128:129], off offset:32
	global_load_dwordx4 v[120:123], v[128:129], off offset:64
	global_load_dwordx4 v[124:127], v[128:129], off offset:96
	s_mul_i32 s56, s26, 0x1800
	s_add_u32 s25, s10, s56
	s_addc_u32 s26, s11, 0
	s_add_u32 s30, s25, s4
	s_addc_u32 s31, s26, 0
	s_add_u32 s28, s30, 0x400
	s_addc_u32 s29, s31, 0
	v_readfirstlane_b32 s24, v215
	s_add_u32 s26, s30, 0x800
	s_addc_u32 s27, s31, 0
	s_lshr_b32 s24, s24, 6
	s_lshl_b32 s25, s24, 3
	v_or_b32_e32 v0, s25, v172
	v_or_b32_e32 v2, s25, v184
	v_lshrrev_b32_e32 v4, 1, v0
	v_mul_lo_u32 v6, v2, s42
	v_xor_b32_e32 v7, v4, v215
	v_or_b32_e32 v2, v6, v194
	v_add_u32_e32 v4, v6, v195
	v_lshlrev_b32_e32 v6, 3, v7
	v_mul_lo_u32 v0, v0, s42
	v_and_b32_e32 v6, 56, v6
	s_lshl_b32 s59, s24, 10
	v_or_b32_e32 v0, v6, v0
	v_mov_b32_e32 v3, v1
	s_lshl_b32 s60, s24, 11
	s_add_i32 s38, s59, 0
	v_lshl_add_u64 v[12:13], v[0:1], 1, s[30:31]
	s_add_i32 s25, s60, 0
	v_lshl_add_u64 v[8:9], v[2:3], 1, s[30:31]
	v_lshl_add_u64 v[12:13], v[12:13], 0, s[6:7]
	s_mov_b32 m0, s38
	v_mov_b32_e32 v5, v1
	v_lshl_add_u64 v[8:9], v[8:9], 0, s[12:13]
	v_lshl_add_u64 v[10:11], v[4:5], 1, s[26:27]
	s_add_i32 s53, s53, 4
	s_barrier
	global_load_lds_dwordx4 v[12:13], off
	s_add_i32 m0, s25, 0x2000
	s_nop 0
	global_load_lds_dwordx4 v[8:9], off
	s_add_i32 m0, s25, 0x2400
	s_cmp_lt_i32 s55, 8
	global_load_lds_dwordx4 v[10:11], off
	s_cselect_b64 s[34:35], -1, 0
	s_cmp_gt_i32 s55, 7
	s_cbranch_scc1 .LBB0_359
	s_add_u32 s62, s26, 0x60000
	v_lshl_add_u64 v[12:13], v[0:1], 1, s[28:29]
	s_addc_u32 s63, s27, 0
	v_lshlrev_b64 v[2:3], 1, v[2:3]
	v_lshl_add_u64 v[14:15], v[12:13], 0, s[14:15]
	s_add_i32 m0, s38, 0x6000
	v_lshl_add_u64 v[10:11], s[62:63], 0, v[2:3]
	global_load_lds_dwordx4 v[14:15], off
	s_add_i32 m0, s25, 0x8000
	v_lshlrev_b64 v[4:5], 1, v[4:5]
	global_load_lds_dwordx4 v[10:11], off
	s_add_i32 m0, s25, 0x8400
	v_lshl_add_u64 v[8:9], s[62:63], 0, v[4:5]
	s_add_u32 s62, s26, 0xc0000
	global_load_lds_dwordx4 v[8:9], off
	s_addc_u32 s63, s27, 0
	v_lshl_add_u64 v[8:9], v[12:13], 0, s[16:17]
	s_add_i32 m0, s38, 0xc000
	v_lshl_add_u64 v[2:3], s[62:63], 0, v[2:3]
	global_load_lds_dwordx4 v[8:9], off
	s_add_i32 m0, s25, 0xe000
	v_lshl_add_u64 v[4:5], s[62:63], 0, v[4:5]
	global_load_lds_dwordx4 v[2:3], off
	s_add_i32 m0, s25, 0xe400
	s_mul_i32 s38, s24, 0x6000
	global_load_lds_dwordx4 v[4:5], off
	s_and_b32 s24, s54, 3
	s_lshl_b32 s61, s55, 2
	v_add_u32_e32 v0, s38, v196
	s_lshl_b32 s24, s24, 8
	v_lshl_add_u64 v[130:131], v[0:1], 1, v[138:139]
	s_add_u32 s24, s56, s24
	v_add_u32_e32 v0, s38, v197
	s_addc_u32 s25, 0, 0
	v_lshl_add_u64 v[146:147], v[0:1], 1, v[138:139]
	v_add3_u32 v0, v188, s38, v6
	v_mov_b32_e32 v14, v1
	v_mov_b32_e32 v15, v1
	s_add_u32 s24, s50, s24
	v_lshl_add_u64 v[148:149], v[0:1], 1, v[140:141]
	v_mov_b32_e32 v0, v1
	v_mov_b32_e32 v2, v1
	v_mov_b32_e32 v3, v1
	v_mov_b32_e32 v4, v1
	v_mov_b32_e32 v5, v1
	v_mov_b32_e32 v6, v1
	v_mov_b32_e32 v7, v1
	v_mov_b32_e32 v8, v1
	v_mov_b32_e32 v9, v1
	v_mov_b32_e32 v10, v1
	v_mov_b32_e32 v11, v1
	v_mov_b32_e32 v12, v1
	v_mov_b32_e32 v13, v1
	v_mov_b64_e32 v[30:31], v[14:15]
	v_mov_b64_e32 v[46:47], v[14:15]
	v_mov_b64_e32 v[62:63], v[14:15]
	v_mov_b64_e32 v[78:79], v[14:15]
	s_addc_u32 s25, s51, s25
	s_sub_i32 s62, 31, s61
	s_mov_b32 s63, 0
	v_mov_b32_e32 v150, 0
	v_mov_b32_e32 v151, 0xf149f2ca
	v_mov_b64_e32 v[28:29], v[12:13]
	v_mov_b64_e32 v[26:27], v[10:11]
	v_mov_b64_e32 v[24:25], v[8:9]
	v_mov_b64_e32 v[22:23], v[6:7]
	v_mov_b64_e32 v[20:21], v[4:5]
	v_mov_b64_e32 v[18:19], v[2:3]
	v_mov_b64_e32 v[16:17], v[0:1]
	v_mov_b64_e32 v[44:45], v[12:13]
	v_mov_b64_e32 v[42:43], v[10:11]
	v_mov_b64_e32 v[40:41], v[8:9]
	v_mov_b64_e32 v[38:39], v[6:7]
	v_mov_b64_e32 v[36:37], v[4:5]
	v_mov_b64_e32 v[34:35], v[2:3]
	v_mov_b64_e32 v[32:33], v[0:1]
	v_mov_b64_e32 v[60:61], v[12:13]
	v_mov_b64_e32 v[58:59], v[10:11]
	v_mov_b64_e32 v[56:57], v[8:9]
	v_mov_b64_e32 v[54:55], v[6:7]
	v_mov_b64_e32 v[52:53], v[4:5]
	v_mov_b64_e32 v[50:51], v[2:3]
	v_mov_b64_e32 v[48:49], v[0:1]
	v_mov_b64_e32 v[76:77], v[12:13]
	v_mov_b64_e32 v[74:75], v[10:11]
	v_mov_b64_e32 v[72:73], v[8:9]
	v_mov_b64_e32 v[70:71], v[6:7]
	v_mov_b64_e32 v[68:69], v[4:5]
	v_mov_b64_e32 v[66:67], v[2:3]
	v_mov_b64_e32 v[64:65], v[0:1]
	s_branch .LBB0_346

.LBB0_380:
	s_and_b32 s30, s28, 7
	s_mul_i32 s4, s30, 0x201
	s_mov_b64 s[12:13], 0
	v_mov_b32_e32 v0, v111
	v_mov_b32_e32 v1, v110
	v_mov_b32_e32 v2, v215
	s_barrier
	v_mul_hi_u32 v3, v215, s21
	v_lshrrev_b32_e32 v3, 9, v3
	v_sub_u32_e32 v4, v110, v3
	v_mad_u32_u24 v4, v3, s22, v4
	v_med3_i32 v4, v4, s23, v114
	v_add_u32_e32 v4, s4, v4
	v_ashrrev_i32_e32 v5, 31, v4
	v_lshl_add_u64 v[4:5], v[4:5], 2, s[66:67]
	global_load_dword v16, v[4:5], off offset:1024
	v_add_u32_e32 v2, 0x200, v215
	v_mul_hi_u32 v3, v2, s21
	v_lshrrev_b32_e32 v3, 9, v3
	v_sub_u32_e32 v6, v110, v3
	v_add_u32_e32 v6, 0xfffffe00, v6
	v_mad_u32_u24 v6, v3, s22, v6
	v_med3_i32 v6, v6, s23, v114
	v_add_u32_e32 v6, s4, v6
	v_ashrrev_i32_e32 v7, 31, v6
	v_lshl_add_u64 v[6:7], v[6:7], 2, s[66:67]
	global_load_dword v17, v[6:7], off offset:1024
	v_add_u32_e32 v2, 0x400, v215
	v_mul_hi_u32 v3, v2, s21
	v_lshrrev_b32_e32 v3, 9, v3
	v_sub_u32_e32 v8, v110, v3
	v_add_u32_e32 v8, 0xfffffc00, v8
	v_mad_u32_u24 v8, v3, s22, v8
	v_med3_i32 v8, v8, s23, v114
	v_add_u32_e32 v8, s4, v8
	v_ashrrev_i32_e32 v9, 31, v8
	v_lshl_add_u64 v[8:9], v[8:9], 2, s[66:67]
	global_load_dword v18, v[8:9], off offset:1024
	v_add_u32_e32 v2, 0x600, v215
	v_mul_hi_u32 v3, v2, s21
	v_lshrrev_b32_e32 v3, 9, v3
	v_sub_u32_e32 v10, v110, v3
	v_add_u32_e32 v10, 0xfffffa00, v10
	v_mad_u32_u24 v10, v3, s22, v10
	v_med3_i32 v10, v10, s23, v114
	v_add_u32_e32 v10, s4, v10
	v_ashrrev_i32_e32 v11, 31, v10
	v_lshl_add_u64 v[10:11], v[10:11], 2, s[66:67]
	global_load_dword v19, v[10:11], off offset:1024
	v_add_u32_e32 v2, 0x800, v215
	v_mul_hi_u32 v3, v2, s21
	v_lshrrev_b32_e32 v3, 9, v3
	v_sub_u32_e32 v12, v110, v3
	v_add_u32_e32 v12, 0xfffff800, v12
	v_mad_u32_u24 v12, v3, s22, v12
	v_med3_i32 v12, v12, s23, v114
	v_add_u32_e32 v12, s4, v12
	v_ashrrev_i32_e32 v13, 31, v12
	v_lshl_add_u64 v[12:13], v[12:13], 2, s[66:67]
	global_load_dword v20, v[12:13], off offset:1024
	v_cmp_gt_u32_e32 vcc, 16, v215
	s_and_saveexec_b64 s[12:13], vcc
	v_add_u32_e32 v2, 0xa00, v215
	v_mul_hi_u32 v3, v2, s21
	v_lshrrev_b32_e32 v3, 9, v3
	v_sub_u32_e32 v14, v110, v3
	v_add_u32_e32 v14, 0xfffff600, v14
	v_mad_u32_u24 v14, v3, s22, v14
	v_med3_i32 v14, v14, s23, v114
	v_add_u32_e32 v14, s4, v14
	v_ashrrev_i32_e32 v15, 31, v14
	v_lshl_add_u64 v[14:15], v[14:15], 2, s[66:67]
	global_load_dword v21, v[14:15], off offset:1024
	s_or_b64 exec, exec, s[12:13]
	s_waitcnt vmcnt(0)
	v_mul_f32_e32 v16, 0x3fb8aa3b, v16
	ds_write_b32 v111, v16
	v_mul_f32_e32 v17, 0x3fb8aa3b, v17
	ds_write_b32 v111, v17 offset:2048
	v_mul_f32_e32 v18, 0x3fb8aa3b, v18
	ds_write_b32 v111, v18 offset:4096
	v_mul_f32_e32 v19, 0x3fb8aa3b, v19
	ds_write_b32 v111, v19 offset:6144
	v_mul_f32_e32 v20, 0x3fb8aa3b, v20
	ds_write_b32 v111, v20 offset:8192
	v_cmp_gt_u32_e32 vcc, 16, v215
	s_and_saveexec_b64 s[12:13], vcc
	v_mul_f32_e32 v21, 0x3fb8aa3b, v21
	ds_write_b32 v111, v21 offset:10240
	s_or_b64 exec, exec, s[12:13]
	s_ashr_i32 s13, s28, 7
	s_lshl_b32 s37, s13, 8
	s_lshl_b32 s4, s28, 8
	s_add_i32 s37, s37, s40
	s_lshl_b32 s12, s13, 2
	s_and_b32 s31, s4, 0x7800
	s_ashr_i32 s29, s37, 31
	s_add_u32 s4, s37, s31
	s_addc_u32 s29, s29, 0
	s_mul_i32 s34, s29, 0x1800
	s_mul_hi_u32 s35, s4, 0x1800
	s_add_i32 s35, s35, s34
	s_mul_i32 s34, s4, 0x1800
	s_add_u32 s34, s10, s34
	s_addc_u32 s35, s11, s35
	s_lshl_b32 s36, s30, 7
	s_add_u32 s34, s34, s36
	s_addc_u32 s35, s35, 0
	v_lshl_add_u64 v[0:1], s[34:35], 0, v[132:133]
	v_lshl_add_u64 v[0:1], v[0:1], 0, v[134:135]
	global_load_dwordx4 v[64:67], v[0:1], off offset:3072
	global_load_dwordx4 v[68:71], v[0:1], off offset:3104
	global_load_dwordx4 v[72:75], v[0:1], off offset:3136
	global_load_dwordx4 v[76:79], v[0:1], off offset:3168
	s_mulk_i32 s31, 0x1800
	s_add_u32 s31, s10, s31
	s_addc_u32 s35, s11, 0
	s_add_u32 s31, s31, s36
	s_addc_u32 s35, s35, 0
	s_add_u32 s43, s31, 0x1000
	s_addc_u32 s44, s35, 0
	v_readfirstlane_b32 s34, v215
	s_add_u32 s36, s31, 0x1400
	s_addc_u32 s38, s35, 0
	s_max_i32 s42, s12, 8
	s_lshr_b32 s39, s34, 6
	s_add_i32 s35, s42, -8
	v_lshl_or_b32 v0, s39, 3, v172
	s_add_i32 s31, s12, 4
	v_lshrrev_b32_e32 v2, 1, v0
	s_mul_i32 s54, s35, 0x60000
	s_mul_hi_u32 s45, s35, 0x60000
	v_xor_b32_e32 v2, v2, v215
	s_add_u32 s52, s43, s54
	v_lshlrev_b32_e32 v2, 3, v2
	s_addc_u32 s53, s44, s45
	s_lshl_b32 s34, s39, 10
	v_mul_lo_u32 v3, v0, s18
	v_and_b32_e32 v32, 56, v2
	s_add_i32 s34, s34, 0
	v_or_b32_e32 v98, v32, v3
	s_add_u32 s54, s36, s54
	v_mov_b32_e32 v1, v99
	v_or_b32_e32 v0, v115, v3
	v_lshl_add_u64 v[2:3], v[98:99], 1, s[52:53]
	s_addc_u32 s55, s38, s45
	s_mov_b32 m0, s34
	v_lshl_add_u64 v[4:5], v[0:1], 1, s[54:55]
	s_add_i32 s45, s42, -7
	s_barrier
	global_load_lds_dwordx4 v[2:3], off
	s_add_i32 m0, s34, 0x2000
	s_cmp_ge_i32 s45, s31
	global_load_lds_dwordx4 v[4:5], off
	s_cbranch_scc1 .LBB0_384
	s_mul_hi_u32 s54, s45, 0x60000
	s_mul_i32 s45, s45, 0x60000
	s_add_u32 s52, s43, s45
	s_addc_u32 s53, s44, s54
	s_add_i32 m0, s34, 0x4000
	v_lshl_add_u64 v[2:3], v[98:99], 1, s[52:53]
	s_add_u32 s52, s36, s45
	s_addc_u32 s53, s38, s54
	global_load_lds_dwordx4 v[2:3], off
	v_lshl_add_u64 v[2:3], v[0:1], 1, s[52:53]
	s_add_i32 m0, s34, 0x6000
	s_nop 0
	global_load_lds_dwordx4 v[2:3], off
